# epilogue re-alignment of the two wave groups extended to P8 (on top of P1/P7)
# speedup vs baseline: 1.0077x; 1.0077x over previous
.Lpeel_out_58:
	s_cmpk_gt_u32 s36, 0xff
	s_cbranch_scc1 .Lep_a_58
	s_barrier
.Lep_a_58:
	v_lshl_add_u32 v146, s61, 8, v142
	v_cvt_pk_bf16_f32 v72, v72, v73
	v_cvt_pk_bf16_f32 v73, v74, v75
	v_cvt_pk_bf16_f32 v74, v68, v69
	v_add_u32_e32 v68, 0x80, v146
	s_lshl_b32 s20, s62, 8
	v_ashrrev_i32_e32 v147, 31, v146
	v_readlane_b32 s22, v252, 10
	v_cvt_pk_bf16_f32 v112, v112, v113
	v_cvt_pk_bf16_f32 v113, v114, v115
	v_cvt_pk_bf16_f32 v114, v108, v109
	v_or_b32_e32 v108, 16, v146
	v_ashrrev_i32_e32 v69, 31, v68
	v_cvt_pk_bf16_f32 v48, v48, v49
	v_cvt_pk_bf16_f32 v49, v50, v51
	v_cvt_pk_bf16_f32 v50, v44, v45
	v_add_u32_e32 v44, 0x90, v146
	s_ashr_i32 s21, s20, 31
	v_lshlrev_b64 v[148:149], 11, v[146:147]
	v_readlane_b32 s23, v252, 11
	v_ashrrev_i32_e32 v109, 31, v108
	v_cvt_pk_bf16_f32 v96, v96, v97
	v_cvt_pk_bf16_f32 v97, v98, v99
	v_cvt_pk_bf16_f32 v98, v92, v93
	v_or_b32_e32 v92, 32, v146
	v_lshlrev_b64 v[68:69], 11, v[68:69]
	v_ashrrev_i32_e32 v45, 31, v44
	v_cvt_pk_bf16_f32 v32, v32, v33
	v_cvt_pk_bf16_f32 v33, v34, v35
	v_cvt_pk_bf16_f32 v34, v28, v29
	v_add_u32_e32 v28, 0xa0, v146
	v_lshl_add_u64 v[148:149], s[22:23], 0, v[148:149]
	s_lshl_b64 s[42:43], s[20:21], 1
	v_lshlrev_b64 v[108:109], 11, v[108:109]
	v_ashrrev_i32_e32 v93, 31, v92
	v_cvt_pk_bf16_f32 v80, v80, v81
	v_cvt_pk_bf16_f32 v81, v82, v83
	v_cvt_pk_bf16_f32 v82, v76, v77
	v_or_b32_e32 v76, 48, v146
	v_lshl_add_u64 v[68:69], s[22:23], 0, v[68:69]
	v_lshlrev_b64 v[44:45], 11, v[44:45]
	v_ashrrev_i32_e32 v29, 31, v28
	v_cvt_pk_bf16_f32 v20, v20, v21
	v_cvt_pk_bf16_f32 v21, v22, v23
	v_cvt_pk_bf16_f32 v22, v12, v13
	v_add_u32_e32 v12, 0xb0, v146
	v_lshl_add_u64 v[148:149], v[148:149], 0, s[42:43]
	v_lshl_add_u64 v[108:109], s[22:23], 0, v[108:109]
	v_lshlrev_b64 v[92:93], 11, v[92:93]
	v_ashrrev_i32_e32 v77, 31, v76
	v_lshl_add_u64 v[68:69], v[68:69], 0, s[42:43]
	v_lshl_add_u64 v[44:45], s[22:23], 0, v[44:45]
	v_lshlrev_b64 v[28:29], 11, v[28:29]
	v_ashrrev_i32_e32 v13, 31, v12
	v_lshl_add_u64 v[148:149], v[148:149], 0, s[72:73]
	v_lshl_add_u64 v[108:109], v[108:109], 0, s[42:43]
	v_lshl_add_u64 v[92:93], s[22:23], 0, v[92:93]
	v_lshlrev_b64 v[76:77], 11, v[76:77]
	v_lshl_add_u64 v[68:69], v[68:69], 0, s[72:73]
	v_lshl_add_u64 v[44:45], v[44:45], 0, s[42:43]
	v_lshl_add_u64 v[28:29], s[22:23], 0, v[28:29]
	v_lshlrev_b64 v[12:13], 11, v[12:13]
	v_lshl_add_u64 v[148:149], v[148:149], 0, v[2:3]
	v_cvt_pk_bf16_f32 v115, v110, v111
	v_lshl_add_u64 v[108:109], v[108:109], 0, s[72:73]
	v_lshl_add_u64 v[92:93], v[92:93], 0, s[42:43]
	v_lshl_add_u64 v[76:77], s[22:23], 0, v[76:77]
	v_lshl_add_u64 v[68:69], v[68:69], 0, v[2:3]
	v_cvt_pk_bf16_f32 v51, v46, v47
	v_lshl_add_u64 v[44:45], v[44:45], 0, s[72:73]
	v_lshl_add_u64 v[28:29], v[28:29], 0, s[42:43]
	v_lshl_add_u64 v[12:13], s[22:23], 0, v[12:13]
	global_store_dwordx4 v[148:149], v[112:115], off offset:256
	v_cvt_pk_bf16_f32 v99, v94, v95
	v_lshl_add_u64 v[92:93], v[92:93], 0, s[72:73]
	v_lshl_add_u64 v[112:113], v[108:109], 0, v[2:3]
	v_lshl_add_u64 v[76:77], v[76:77], 0, s[42:43]
	global_store_dwordx4 v[68:69], v[48:51], off offset:256
	v_cvt_pk_bf16_f32 v35, v30, v31
	v_lshl_add_u64 v[28:29], v[28:29], 0, s[72:73]
	v_lshl_add_u64 v[48:49], v[44:45], 0, v[2:3]
	v_lshl_add_u64 v[12:13], v[12:13], 0, s[42:43]
	global_store_dwordx4 v[112:113], v[96:99], off offset:256
	v_cvt_pk_bf16_f32 v83, v78, v79
	v_lshl_add_u64 v[76:77], v[76:77], 0, s[72:73]
	v_lshl_add_u64 v[96:97], v[92:93], 0, v[2:3]
	global_store_dwordx4 v[48:49], v[32:35], off offset:256
	v_cvt_pk_bf16_f32 v23, v14, v15
	v_lshl_add_u64 v[12:13], v[12:13], 0, s[72:73]
	v_lshl_add_u64 v[32:33], v[28:29], 0, v[2:3]
	v_cvt_pk_bf16_f32 v128, v128, v129
	v_cvt_pk_bf16_f32 v129, v130, v131
	v_cvt_pk_bf16_f32 v130, v124, v125
	v_cvt_pk_bf16_f32 v131, v126, v127
	v_cvt_pk_bf16_f32 v108, v120, v121
	v_cvt_pk_bf16_f32 v109, v122, v123
	v_cvt_pk_bf16_f32 v110, v116, v117
	v_cvt_pk_bf16_f32 v111, v118, v119
	v_cvt_pk_bf16_f32 v92, v104, v105
	v_cvt_pk_bf16_f32 v93, v106, v107
	v_cvt_pk_bf16_f32 v94, v100, v101
	v_cvt_pk_bf16_f32 v95, v102, v103
	global_store_dwordx4 v[96:97], v[80:83], off offset:256
	v_cvt_pk_bf16_f32 v78, v84, v85
	v_cvt_pk_bf16_f32 v79, v86, v87
	v_lshl_add_u64 v[80:81], v[76:77], 0, v[2:3]
	v_cvt_pk_bf16_f32 v76, v88, v89
	v_cvt_pk_bf16_f32 v77, v90, v91
	v_cvt_pk_bf16_f32 v75, v70, v71
	v_cvt_pk_bf16_f32 v64, v64, v65
	v_cvt_pk_bf16_f32 v65, v66, v67
	v_cvt_pk_bf16_f32 v66, v60, v61
	v_cvt_pk_bf16_f32 v67, v62, v63
	v_cvt_pk_bf16_f32 v44, v56, v57
	v_cvt_pk_bf16_f32 v45, v58, v59
	v_cvt_pk_bf16_f32 v46, v52, v53
	v_cvt_pk_bf16_f32 v47, v54, v55
	v_cvt_pk_bf16_f32 v28, v40, v41
	v_cvt_pk_bf16_f32 v29, v42, v43
	v_cvt_pk_bf16_f32 v30, v36, v37
	v_cvt_pk_bf16_f32 v31, v38, v39
	global_store_dwordx4 v[32:33], v[20:23], off offset:256
	v_cvt_pk_bf16_f32 v14, v16, v17
	v_cvt_pk_bf16_f32 v15, v18, v19
	v_lshl_add_u64 v[20:21], v[12:13], 0, v[2:3]
	v_cvt_pk_bf16_f32 v12, v24, v25
	v_cvt_pk_bf16_f32 v13, v26, v27
	v_cvt_pk_bf16_f32 v8, v8, v9
	v_cvt_pk_bf16_f32 v9, v10, v11
	v_cvt_pk_bf16_f32 v10, v4, v5
	v_cvt_pk_bf16_f32 v11, v6, v7
	s_and_b64 vcc, exec, s[38:39]
	s_mov_b32 s62, s59
	s_mov_b32 s61, s60
	s_mov_b64 s[44:45], s[40:41]
	s_mov_b64 s[42:43], s[0:1]
	global_store_dwordx4 v[148:149], v[128:131], off
	global_store_dwordx4 v[112:113], v[108:111], off
	global_store_dwordx4 v[96:97], v[92:95], off
	global_store_dwordx4 v[80:81], v[76:79], off
	global_store_dwordx4 v[80:81], v[72:75], off offset:256
	global_store_dwordx4 v[68:69], v[64:67], off
	global_store_dwordx4 v[48:49], v[44:47], off
	global_store_dwordx4 v[32:33], v[28:31], off
	global_store_dwordx4 v[20:21], v[12:15], off
	global_store_dwordx4 v[20:21], v[8:11], off offset:256
	s_cmpk_lt_u32 s36, 0x100
	s_cbranch_scc1 .Lep_b_58
	s_barrier
.Lep_b_58:
	s_cbranch_vccz .LBB0_51
	s_waitcnt vmcnt(0)
	s_cmpk_gt_u32 s36, 0xff
	s_cbranch_scc1 .LBB0_62
	s_barrier
